# nt hint extended: out-proj layer-0 residual (module input) loads, final y output stores, samp_b conv-cache output store
# speedup vs baseline: 1.0161x; 1.0099x over previous
.LBB0_90:
	s_add_i32 s2, s2, s65
	v_add_u32_e32 v178, s2, v144
	s_load_dwordx2 s[2:3], s[18:19], 0x0
	v_and_b32_e32 v201, 1, v144
	v_lshl_or_b32 v146, v201, 2, v200
	v_and_b32_e32 v202, -2, v178
	v_ashrrev_i32_e32 v147, 31, v146
	v_ashrrev_i32_e32 v203, 31, v202
	s_waitcnt lgkmcnt(0)
	v_lshl_add_u64 v[196:197], v[146:147], 2, s[2:3]
	v_lshlrev_b64 v[144:145], 12, v[202:203]
	v_lshl_add_u64 v[144:145], v[196:197], 0, v[144:145]
	s_movk_i32 s2, 0x1000
	v_add_co_u32_e32 v146, vcc, s2, v144
	s_nop 1
	v_addc_co_u32_e32 v147, vcc, 0, v145, vcc
	global_load_dwordx4 v[218:221], v[144:145], off nt
	global_load_dwordx4 v[160:163], v[144:145], off offset:128 nt
	global_load_dwordx4 v[240:243], v[146:147], off nt
	global_load_dwordx4 v[164:167], v[146:147], off offset:128 nt
	v_add_u32_e32 v144, 16, v178
	v_and_b32_e32 v198, -2, v144
	v_ashrrev_i32_e32 v199, 31, v198
	v_lshlrev_b64 v[144:145], 12, v[198:199]
	v_lshl_add_u64 v[144:145], v[196:197], 0, v[144:145]
	v_add_co_u32_e32 v148, vcc, s2, v144
	v_cmp_eq_u32_e64 s[2:3], 0, v201
	s_nop 0
	v_addc_co_u32_e32 v149, vcc, 0, v145, vcc
	global_load_dwordx4 v[152:155], v[144:145], off nt
	s_nop 0
	global_load_dwordx4 v[144:147], v[144:145], off offset:128 nt
	s_nop 0
	global_load_dwordx4 v[156:159], v[148:149], off nt
	s_nop 0
	global_load_dwordx4 v[148:151], v[148:149], off offset:128 nt
	s_waitcnt vmcnt(0)
	v_cndmask_b32_e64 v210, v218, v240, s[2:3]
	v_cndmask_b32_e64 v211, v219, v241, s[2:3]
	v_cndmask_b32_e64 v217, v220, v242, s[2:3]
	v_cndmask_b32_e64 v223, v221, v243, s[2:3]
	v_mov_b32_dpp v210, v210 quad_perm:[1,0,3,2] row_mask:0xf bank_mask:0xf bound_ctrl:1
	v_mov_b32_dpp v211, v211 quad_perm:[1,0,3,2] row_mask:0xf bank_mask:0xf bound_ctrl:1
	v_mov_b32_dpp v217, v217 quad_perm:[1,0,3,2] row_mask:0xf bank_mask:0xf bound_ctrl:1
	v_mov_b32_dpp v223, v223 quad_perm:[1,0,3,2] row_mask:0xf bank_mask:0xf bound_ctrl:1
	v_cndmask_b32_e64 v218, v210, v218, s[2:3]
	v_cndmask_b32_e64 v224, v240, v210, s[2:3]
	v_cndmask_b32_e64 v219, v211, v219, s[2:3]
	v_cndmask_b32_e64 v225, v241, v211, s[2:3]
	v_cndmask_b32_e64 v220, v217, v220, s[2:3]
	v_cndmask_b32_e64 v240, v242, v217, s[2:3]
	v_cndmask_b32_e64 v221, v223, v221, s[2:3]
	v_cndmask_b32_e64 v241, v243, v223, s[2:3]
	v_pk_fma_f32 v[142:143], v[142:143], v[62:63], v[220:221]
	v_pk_fma_f32 v[140:141], v[140:141], v[60:61], v[218:219]
	v_pk_fma_f32 v[138:139], v[138:139], v[58:59], v[240:241]
	v_pk_fma_f32 v[136:137], v[136:137], v[56:57], v[224:225]
	s_and_b64 vcc, exec, s[0:1]
	v_mov_b32_e32 v224, 0
	v_mov_b32_e32 v225, 0
	v_mov_b32_e32 v217, 0
	v_mov_b32_e32 v219, 0
	v_cvt_pk_bf16_f32 v223, v140, v141
	v_cvt_pk_bf16_f32 v221, v142, v143
	v_cvt_pk_bf16_f32 v220, v136, v137
	v_cvt_pk_bf16_f32 v218, v138, v139
	s_cbranch_vccnz .LBB0_92
	v_mov_b32_e32 v240, v141
	v_mov_b32_e32 v241, v137
	v_mov_b32_e32 v244, v143
	v_mov_b32_e32 v245, v139
	v_mov_b32_e32 v224, v140
	v_mov_b32_e32 v225, v136
	v_pk_mul_f32 v[240:241], v[240:241], v[240:241]
	v_mov_b32_e32 v242, v142
	v_mov_b32_e32 v243, v138
	v_pk_mul_f32 v[244:245], v[244:245], v[244:245]
	v_pk_fma_f32 v[224:225], v[224:225], v[224:225], v[240:241]
	v_pk_fma_f32 v[240:241], v[242:243], v[242:243], v[244:245]
	v_pk_mul_f32 v[142:143], v[190:191], v[142:143]
	v_pk_add_f32 v[224:225], v[224:225], v[240:241]
	v_pk_mul_f32 v[140:141], v[188:189], v[140:141]
	v_add_f32_e32 v179, v224, v225
	v_pk_mul_f32 v[138:139], v[186:187], v[138:139]
	v_pk_mul_f32 v[136:137], v[184:185], v[136:137]
	v_cvt_pk_bf16_f32 v224, v140, v141
	v_cvt_pk_bf16_f32 v225, v142, v143
	s_nop 0
	v_cvt_pk_bf16_f32 v217, v136, v137
	v_cvt_pk_bf16_f32 v219, v138, v139

.LBB0_108:
	v_add_u32_e32 v112, 32, v178
	v_and_b32_e32 v140, -2, v112
	v_ashrrev_i32_e32 v141, 31, v140
	s_waitcnt lgkmcnt(0)
	v_lshlrev_b64 v[112:113], 12, v[140:141]
	v_lshl_add_u64 v[112:113], v[196:197], 0, v[112:113]
	v_add_co_u32_e32 v114, vcc, 0x1000, v112
	s_movk_i32 s22, 0x1000
	s_nop 0
	v_addc_co_u32_e32 v115, vcc, 0, v113, vcc
	global_load_dwordx4 v[142:145], v[112:113], off nt
	global_load_dwordx4 v[128:131], v[112:113], off offset:128 nt
	global_load_dwordx4 v[146:149], v[114:115], off nt
	global_load_dwordx4 v[132:135], v[114:115], off offset:128 nt
	v_add_u32_e32 v112, 48, v178
	v_and_b32_e32 v138, -2, v112
	v_ashrrev_i32_e32 v139, 31, v138
	v_lshlrev_b64 v[112:113], 12, v[138:139]
	v_lshl_add_u64 v[112:113], v[196:197], 0, v[112:113]
	v_add_co_u32_e32 v116, vcc, s22, v112
	s_nop 1
	v_addc_co_u32_e32 v117, vcc, 0, v113, vcc
	global_load_dwordx4 v[120:123], v[112:113], off nt
	s_nop 0
	global_load_dwordx4 v[112:115], v[112:113], off offset:128 nt
	s_nop 0
	global_load_dwordx4 v[124:127], v[116:117], off nt
	s_nop 0
	global_load_dwordx4 v[116:119], v[116:117], off offset:128 nt
	s_waitcnt vmcnt(5)
	v_cndmask_b32_e64 v150, v142, v146, s[2:3]
	v_cndmask_b32_e64 v151, v143, v147, s[2:3]
	v_cndmask_b32_e64 v152, v144, v148, s[2:3]
	v_cndmask_b32_e64 v153, v145, v149, s[2:3]
	v_mov_b32_dpp v150, v150 quad_perm:[1,0,3,2] row_mask:0xf bank_mask:0xf bound_ctrl:1
	v_mov_b32_dpp v151, v151 quad_perm:[1,0,3,2] row_mask:0xf bank_mask:0xf bound_ctrl:1
	v_mov_b32_dpp v152, v152 quad_perm:[1,0,3,2] row_mask:0xf bank_mask:0xf bound_ctrl:1
	v_mov_b32_dpp v153, v153 quad_perm:[1,0,3,2] row_mask:0xf bank_mask:0xf bound_ctrl:1
	v_cndmask_b32_e64 v142, v150, v142, s[2:3]
	v_cndmask_b32_e64 v146, v146, v150, s[2:3]
	v_cndmask_b32_e64 v143, v151, v143, s[2:3]
	v_cndmask_b32_e64 v147, v147, v151, s[2:3]
	v_cndmask_b32_e64 v144, v152, v144, s[2:3]
	v_cndmask_b32_e64 v148, v148, v152, s[2:3]
	v_cndmask_b32_e64 v145, v153, v145, s[2:3]
	v_cndmask_b32_e64 v149, v149, v153, s[2:3]
	v_pk_fma_f32 v[110:111], v[110:111], v[62:63], v[144:145]
	v_pk_fma_f32 v[108:109], v[108:109], v[60:61], v[142:143]
	v_pk_fma_f32 v[106:107], v[106:107], v[58:59], v[148:149]
	v_pk_fma_f32 v[104:105], v[104:105], v[56:57], v[146:147]
	v_mov_b32_e32 v149, 0
	s_and_b64 vcc, exec, s[0:1]
	v_mov_b32_e32 v142, 0
	v_mov_b32_e32 v150, 0
	v_mov_b32_e32 v151, 0
	v_mov_b32_e32 v143, 0
	v_mov_b32_e32 v146, 0
	v_cvt_pk_bf16_f32 v148, v108, v109
	v_cvt_pk_bf16_f32 v147, v110, v111
	v_cvt_pk_bf16_f32 v145, v104, v105
	v_cvt_pk_bf16_f32 v144, v106, v107
	s_cbranch_vccnz .LBB0_110
	v_mov_b32_e32 v150, v109
	v_mov_b32_e32 v151, v105
	v_mov_b32_e32 v154, v111
	v_mov_b32_e32 v155, v107
	v_mov_b32_e32 v142, v108
	v_mov_b32_e32 v143, v104
	v_pk_mul_f32 v[150:151], v[150:151], v[150:151]
	v_mov_b32_e32 v152, v110
	v_mov_b32_e32 v153, v106
	v_pk_mul_f32 v[154:155], v[154:155], v[154:155]
	v_pk_fma_f32 v[142:143], v[142:143], v[142:143], v[150:151]
	v_pk_fma_f32 v[150:151], v[152:153], v[152:153], v[154:155]
	v_pk_mul_f32 v[110:111], v[190:191], v[110:111]
	v_pk_add_f32 v[142:143], v[142:143], v[150:151]
	v_pk_mul_f32 v[108:109], v[188:189], v[108:109]
	v_add_f32_e32 v142, v142, v143
	v_pk_mul_f32 v[106:107], v[186:187], v[106:107]
	v_pk_mul_f32 v[104:105], v[184:185], v[104:105]
	v_cvt_pk_bf16_f32 v150, v108, v109
	v_cvt_pk_bf16_f32 v151, v110, v111
	s_nop 0
	v_cvt_pk_bf16_f32 v143, v104, v105
	v_cvt_pk_bf16_f32 v146, v106, v107

.LBB0_126:
	v_add_u32_e32 v80, 0x80, v178
	v_and_b32_e32 v106, -2, v80
	v_ashrrev_i32_e32 v107, 31, v106
	s_waitcnt lgkmcnt(0)
	v_lshlrev_b64 v[80:81], 12, v[106:107]
	v_lshl_add_u64 v[80:81], v[196:197], 0, v[80:81]
	v_add_co_u32_e32 v82, vcc, 0x1000, v80
	s_movk_i32 s22, 0x1000
	s_nop 0
	v_addc_co_u32_e32 v83, vcc, 0, v81, vcc
	global_load_dwordx4 v[108:111], v[80:81], off nt
	global_load_dwordx4 v[96:99], v[80:81], off offset:128 nt
	global_load_dwordx4 v[112:115], v[82:83], off nt
	global_load_dwordx4 v[100:103], v[82:83], off offset:128 nt
	v_add_u32_e32 v80, 0x90, v178
	v_and_b32_e32 v104, -2, v80
	v_ashrrev_i32_e32 v105, 31, v104
	v_lshlrev_b64 v[80:81], 12, v[104:105]
	v_lshl_add_u64 v[80:81], v[196:197], 0, v[80:81]
	v_add_co_u32_e32 v84, vcc, s22, v80
	s_nop 1
	v_addc_co_u32_e32 v85, vcc, 0, v81, vcc
	global_load_dwordx4 v[88:91], v[80:81], off nt
	s_nop 0
	global_load_dwordx4 v[80:83], v[80:81], off offset:128 nt
	s_nop 0
	global_load_dwordx4 v[92:95], v[84:85], off nt
	s_nop 0
	global_load_dwordx4 v[84:87], v[84:85], off offset:128 nt
	s_waitcnt vmcnt(5)
	v_cndmask_b32_e64 v116, v108, v112, s[2:3]
	v_cndmask_b32_e64 v117, v109, v113, s[2:3]
	v_cndmask_b32_e64 v118, v110, v114, s[2:3]
	v_cndmask_b32_e64 v119, v111, v115, s[2:3]
	v_mov_b32_dpp v116, v116 quad_perm:[1,0,3,2] row_mask:0xf bank_mask:0xf bound_ctrl:1
	v_mov_b32_dpp v117, v117 quad_perm:[1,0,3,2] row_mask:0xf bank_mask:0xf bound_ctrl:1
	v_mov_b32_dpp v118, v118 quad_perm:[1,0,3,2] row_mask:0xf bank_mask:0xf bound_ctrl:1
	v_mov_b32_dpp v119, v119 quad_perm:[1,0,3,2] row_mask:0xf bank_mask:0xf bound_ctrl:1
	v_cndmask_b32_e64 v108, v116, v108, s[2:3]
	v_cndmask_b32_e64 v112, v112, v116, s[2:3]
	v_cndmask_b32_e64 v109, v117, v109, s[2:3]
	v_cndmask_b32_e64 v113, v113, v117, s[2:3]
	v_cndmask_b32_e64 v110, v118, v110, s[2:3]
	v_cndmask_b32_e64 v114, v114, v118, s[2:3]
	v_cndmask_b32_e64 v111, v119, v111, s[2:3]
	v_cndmask_b32_e64 v115, v115, v119, s[2:3]
	v_pk_fma_f32 v[78:79], v[78:79], v[62:63], v[110:111]
	v_pk_fma_f32 v[76:77], v[76:77], v[60:61], v[108:109]
	v_pk_fma_f32 v[74:75], v[74:75], v[58:59], v[114:115]
	v_pk_fma_f32 v[72:73], v[72:73], v[56:57], v[112:113]
	v_mov_b32_e32 v115, 0
	s_and_b64 vcc, exec, s[0:1]
	v_mov_b32_e32 v108, 0
	v_mov_b32_e32 v116, 0
	v_mov_b32_e32 v117, 0
	v_mov_b32_e32 v109, 0
	v_mov_b32_e32 v112, 0
	v_cvt_pk_bf16_f32 v114, v76, v77
	v_cvt_pk_bf16_f32 v113, v78, v79
	v_cvt_pk_bf16_f32 v111, v72, v73
	v_cvt_pk_bf16_f32 v110, v74, v75
	s_cbranch_vccnz .LBB0_128
	v_mov_b32_e32 v116, v77
	v_mov_b32_e32 v117, v73
	v_mov_b32_e32 v120, v79
	v_mov_b32_e32 v121, v75
	v_mov_b32_e32 v108, v76
	v_mov_b32_e32 v109, v72
	v_pk_mul_f32 v[116:117], v[116:117], v[116:117]
	v_mov_b32_e32 v118, v78
	v_mov_b32_e32 v119, v74
	v_pk_mul_f32 v[120:121], v[120:121], v[120:121]
	v_pk_fma_f32 v[108:109], v[108:109], v[108:109], v[116:117]
	v_pk_fma_f32 v[116:117], v[118:119], v[118:119], v[120:121]
	v_pk_mul_f32 v[78:79], v[190:191], v[78:79]
	v_pk_add_f32 v[108:109], v[108:109], v[116:117]
	v_pk_mul_f32 v[76:77], v[188:189], v[76:77]
	v_add_f32_e32 v108, v108, v109
	v_pk_mul_f32 v[74:75], v[186:187], v[74:75]
	v_pk_mul_f32 v[72:73], v[184:185], v[72:73]
	v_cvt_pk_bf16_f32 v116, v76, v77
	v_cvt_pk_bf16_f32 v117, v78, v79
	s_nop 0
	v_cvt_pk_bf16_f32 v109, v72, v73
	v_cvt_pk_bf16_f32 v112, v74, v75

.LBB0_144:
	v_add_u32_e32 v32, 0xa0, v178
	v_and_b32_e32 v74, -2, v32
	v_ashrrev_i32_e32 v75, 31, v74
	s_waitcnt lgkmcnt(0)
	v_lshlrev_b64 v[32:33], 12, v[74:75]
	v_lshl_add_u64 v[32:33], v[196:197], 0, v[32:33]
	v_add_co_u32_e32 v34, vcc, 0x1000, v32
	s_movk_i32 s22, 0x1000
	s_nop 0
	v_addc_co_u32_e32 v35, vcc, 0, v33, vcc
	global_load_dwordx4 v[76:79], v[32:33], off nt
	global_load_dwordx4 v[64:67], v[32:33], off offset:128 nt
	global_load_dwordx4 v[80:83], v[34:35], off nt
	global_load_dwordx4 v[68:71], v[34:35], off offset:128 nt
	v_add_u32_e32 v32, 0xb0, v178
	v_and_b32_e32 v72, -2, v32
	v_ashrrev_i32_e32 v73, 31, v72
	v_lshlrev_b64 v[32:33], 12, v[72:73]
	v_lshl_add_u64 v[32:33], v[196:197], 0, v[32:33]
	v_add_co_u32_e32 v36, vcc, s22, v32
	s_nop 1
	v_addc_co_u32_e32 v37, vcc, 0, v33, vcc
	global_load_dwordx4 v[44:47], v[32:33], off nt
	s_nop 0
	global_load_dwordx4 v[32:35], v[32:33], off offset:128 nt
	s_nop 0
	global_load_dwordx4 v[52:55], v[36:37], off nt
	s_nop 0
	global_load_dwordx4 v[36:39], v[36:37], off offset:128 nt
	s_waitcnt vmcnt(5)
	v_cndmask_b32_e64 v84, v76, v80, s[2:3]
	v_cndmask_b32_e64 v85, v77, v81, s[2:3]
	v_cndmask_b32_e64 v86, v78, v82, s[2:3]
	v_cndmask_b32_e64 v87, v79, v83, s[2:3]
	v_mov_b32_dpp v84, v84 quad_perm:[1,0,3,2] row_mask:0xf bank_mask:0xf bound_ctrl:1
	v_mov_b32_dpp v85, v85 quad_perm:[1,0,3,2] row_mask:0xf bank_mask:0xf bound_ctrl:1
	v_mov_b32_dpp v86, v86 quad_perm:[1,0,3,2] row_mask:0xf bank_mask:0xf bound_ctrl:1
	v_mov_b32_dpp v87, v87 quad_perm:[1,0,3,2] row_mask:0xf bank_mask:0xf bound_ctrl:1
	v_cndmask_b32_e64 v76, v84, v76, s[2:3]
	v_cndmask_b32_e64 v80, v80, v84, s[2:3]
	v_cndmask_b32_e64 v77, v85, v77, s[2:3]
	v_cndmask_b32_e64 v81, v81, v85, s[2:3]
	v_cndmask_b32_e64 v78, v86, v78, s[2:3]
	v_cndmask_b32_e64 v82, v82, v86, s[2:3]
	v_cndmask_b32_e64 v79, v87, v79, s[2:3]
	v_cndmask_b32_e64 v83, v83, v87, s[2:3]
	v_pk_fma_f32 v[30:31], v[30:31], v[62:63], v[78:79]
	v_pk_fma_f32 v[28:29], v[28:29], v[60:61], v[76:77]
	v_pk_fma_f32 v[26:27], v[26:27], v[58:59], v[82:83]
	v_pk_fma_f32 v[24:25], v[24:25], v[56:57], v[80:81]
	v_mov_b32_e32 v83, 0
	s_and_b64 vcc, exec, s[0:1]
	v_mov_b32_e32 v76, 0
	v_mov_b32_e32 v84, 0
	v_mov_b32_e32 v85, 0
	v_mov_b32_e32 v77, 0
	v_mov_b32_e32 v80, 0
	v_cvt_pk_bf16_f32 v82, v28, v29
	v_cvt_pk_bf16_f32 v81, v30, v31
	v_cvt_pk_bf16_f32 v79, v24, v25
	v_cvt_pk_bf16_f32 v78, v26, v27
	s_cbranch_vccnz .LBB0_146
	v_mov_b32_e32 v84, v29
	v_mov_b32_e32 v85, v25
	v_mov_b32_e32 v88, v31
	v_mov_b32_e32 v89, v27
	v_mov_b32_e32 v76, v28
	v_mov_b32_e32 v77, v24
	v_pk_mul_f32 v[84:85], v[84:85], v[84:85]
	v_mov_b32_e32 v86, v30
	v_mov_b32_e32 v87, v26
	v_pk_mul_f32 v[88:89], v[88:89], v[88:89]
	v_pk_fma_f32 v[76:77], v[76:77], v[76:77], v[84:85]
	v_pk_fma_f32 v[84:85], v[86:87], v[86:87], v[88:89]
	v_pk_mul_f32 v[30:31], v[190:191], v[30:31]
	v_pk_add_f32 v[76:77], v[76:77], v[84:85]
	v_pk_mul_f32 v[28:29], v[188:189], v[28:29]
	v_add_f32_e32 v76, v76, v77
	v_pk_mul_f32 v[26:27], v[186:187], v[26:27]
	v_pk_mul_f32 v[24:25], v[184:185], v[24:25]
	v_cvt_pk_bf16_f32 v84, v28, v29
	v_cvt_pk_bf16_f32 v85, v30, v31
	s_nop 0
	v_cvt_pk_bf16_f32 v77, v24, v25
	v_cvt_pk_bf16_f32 v80, v26, v27

.LBB0_284:
	s_barrier
	v_readlane_b32 s0, v252, 2
	v_lshlrev_b32_e32 v111, 3, v179
	v_add_u32_e32 v0, s27, v111
	v_add_u32_e32 v114, s17, v178
	v_ashrrev_i32_e32 v1, 31, v0
	v_ashrrev_i32_e32 v115, 31, v114
	v_lshl_add_u64 v[4:5], v[0:1], 2, s[2:3]
	v_lshl_add_u64 v[106:107], v[114:115], 2, s[14:15]
	global_load_dwordx4 v[8:11], v[4:5], off offset:16
	global_load_dwordx4 v[12:15], v[4:5], off
	global_load_dwordx4 v[0:3], v[4:5], off offset:144
	s_nop 0
	global_load_dwordx4 v[4:7], v[4:5], off offset:128
	s_nop 0
	global_load_dword v110, v[106:107], off
	global_load_dword v115, v[106:107], off offset:64
	global_load_dword v118, v[106:107], off offset:128
	global_load_dword v119, v[106:107], off offset:192
	global_load_dword v144, v[106:107], off offset:512
	global_load_dword v145, v[106:107], off offset:576
	global_load_dword v147, v[106:107], off offset:640
	s_nop 0
	global_load_dword v106, v[106:107], off offset:704
	v_and_b32_e32 v114, -2, v114
	v_readlane_b32 s1, v252, 3
	s_waitcnt vmcnt(7)
	v_fmamk_f32 v107, v110, 0x3a800000, v222
	v_rsq_f32_e32 v170, v107
	s_waitcnt vmcnt(6)
	v_fmamk_f32 v107, v115, 0x3a800000, v222
	v_rsq_f32_e32 v150, v107
	s_waitcnt vmcnt(5)
	v_fmamk_f32 v107, v118, 0x3a800000, v222
	v_rsq_f32_e32 v148, v107
	s_waitcnt vmcnt(4)
	v_fmamk_f32 v107, v119, 0x3a800000, v222
	v_rsq_f32_e32 v146, v107
	s_waitcnt vmcnt(3)
	v_fmamk_f32 v107, v144, 0x3a800000, v222
	v_rsq_f32_e32 v144, v107
	s_waitcnt vmcnt(2)
	v_fmamk_f32 v107, v145, 0x3a800000, v222
	v_ashrrev_i32_e32 v115, 31, v114
	v_rsq_f32_e32 v118, v107
	s_waitcnt vmcnt(1)
	v_fmamk_f32 v107, v147, 0x3a800000, v222
	v_lshlrev_b64 v[114:115], 12, v[114:115]
	v_rsq_f32_e32 v110, v107
	v_and_b32_e32 v107, 1, v178
	v_lshl_add_u64 v[114:115], s[0:1], 0, v[114:115]
	v_lshl_or_b32 v172, v107, 2, v111
	v_lshl_add_u64 v[114:115], s[34:35], 2, v[114:115]
	v_ashrrev_i32_e32 v173, 31, v172
	v_lshl_add_u64 v[114:115], v[114:115], 0, s[54:55]
	v_pk_mul_f32 v[164:165], v[164:165], v[170:171] op_sel_hi:[1,0]
	v_pk_mul_f32 v[162:163], v[162:163], v[170:171] op_sel_hi:[1,0]
	v_lshl_add_u64 v[114:115], v[172:173], 2, v[114:115]
	v_pk_mul_f32 v[172:173], v[14:15], v[162:163]
	v_pk_mul_f32 v[162:163], v[12:13], v[164:165]
	v_pk_mul_f32 v[164:165], v[168:169], v[170:171] op_sel_hi:[1,0]
	v_pk_mul_f32 v[166:167], v[166:167], v[170:171] op_sel_hi:[1,0]
	v_cmp_eq_u32_e32 vcc, 0, v107
	v_pk_mul_f32 v[168:169], v[10:11], v[166:167]
	v_pk_mul_f32 v[164:165], v[8:9], v[164:165]
	v_cndmask_b32_e32 v119, v172, v168, vcc
	v_cndmask_b32_e32 v107, v162, v164, vcc
	v_cndmask_b32_e32 v111, v163, v165, vcc
	v_cndmask_b32_e32 v145, v173, v169, vcc
	v_mov_b32_dpp v107, v107 quad_perm:[1,0,3,2] row_mask:0xf bank_mask:0xf bound_ctrl:1
	v_mov_b32_dpp v111, v111 quad_perm:[1,0,3,2] row_mask:0xf bank_mask:0xf bound_ctrl:1
	v_mov_b32_dpp v119, v119 quad_perm:[1,0,3,2] row_mask:0xf bank_mask:0xf bound_ctrl:1
	v_mov_b32_dpp v145, v145 quad_perm:[1,0,3,2] row_mask:0xf bank_mask:0xf bound_ctrl:1
	v_cndmask_b32_e32 v162, v107, v162, vcc
	v_cndmask_b32_e32 v166, v164, v107, vcc
	v_cndmask_b32_e32 v163, v111, v163, vcc
	v_cndmask_b32_e32 v167, v165, v111, vcc
	v_cndmask_b32_e32 v164, v119, v172, vcc
	v_cndmask_b32_e32 v165, v145, v173, vcc
	v_pk_mul_f32 v[142:143], v[142:143], v[170:171] op_sel_hi:[1,0]
	v_pk_mul_f32 v[138:139], v[138:139], v[170:171] op_sel_hi:[1,0]
	v_pk_mul_f32 v[140:141], v[140:141], v[170:171] op_sel_hi:[1,0]
	v_pk_mul_f32 v[136:137], v[136:137], v[170:171] op_sel_hi:[1,0]
	global_store_dwordx4 v[114:115], v[162:165], off nt
	v_pk_mul_f32 v[138:139], v[6:7], v[138:139]
	v_pk_mul_f32 v[142:143], v[4:5], v[142:143]
	v_pk_mul_f32 v[164:165], v[2:3], v[136:137]
	v_pk_mul_f32 v[140:141], v[0:1], v[140:141]
	v_cndmask_b32_e32 v168, v168, v119, vcc
	s_movk_i32 s0, 0x1000
	v_cndmask_b32_e32 v107, v142, v140, vcc
	v_cndmask_b32_e32 v111, v143, v141, vcc
	v_cndmask_b32_e32 v119, v138, v164, vcc
	v_cndmask_b32_e32 v136, v139, v165, vcc
	v_cndmask_b32_e32 v169, v169, v145, vcc
	v_add_co_u32_e64 v162, s[0:1], s0, v114
	v_mov_b32_dpp v107, v107 quad_perm:[1,0,3,2] row_mask:0xf bank_mask:0xf bound_ctrl:1
	v_mov_b32_dpp v111, v111 quad_perm:[1,0,3,2] row_mask:0xf bank_mask:0xf bound_ctrl:1
	v_mov_b32_dpp v119, v119 quad_perm:[1,0,3,2] row_mask:0xf bank_mask:0xf bound_ctrl:1
	v_mov_b32_dpp v145, v136 quad_perm:[1,0,3,2] row_mask:0xf bank_mask:0xf bound_ctrl:1
	v_pk_mul_f32 v[130:131], v[130:131], v[150:151] op_sel_hi:[1,0]
	v_pk_mul_f32 v[134:135], v[134:135], v[150:151] op_sel_hi:[1,0]
	v_addc_co_u32_e64 v163, s[0:1], 0, v115, s[0:1]
	v_cndmask_b32_e32 v136, v107, v142, vcc
	v_cndmask_b32_e32 v137, v111, v143, vcc
	v_cndmask_b32_e32 v138, v119, v138, vcc
	v_cndmask_b32_e32 v139, v145, v139, vcc
	v_pk_mul_f32 v[126:127], v[126:127], v[150:151] op_sel_hi:[1,0]
	v_pk_mul_f32 v[130:131], v[12:13], v[130:131]
	v_pk_mul_f32 v[124:125], v[124:125], v[150:151] op_sel_hi:[1,0]
	v_pk_mul_f32 v[134:135], v[8:9], v[134:135]
	global_store_dwordx4 v[162:163], v[166:169], off nt
	v_cndmask_b32_e32 v140, v140, v107, vcc
	v_cndmask_b32_e32 v141, v141, v111, vcc
	v_cndmask_b32_e32 v142, v164, v119, vcc
	v_cndmask_b32_e32 v143, v165, v145, vcc
	global_store_dwordx4 v[114:115], v[136:139], off offset:128 nt
	global_store_dwordx4 v[162:163], v[140:143], off offset:128 nt
	s_mov_b64 s[0:1], 0x10000
	v_pk_mul_f32 v[126:127], v[14:15], v[126:127]
	v_pk_mul_f32 v[136:137], v[10:11], v[124:125]
	v_cndmask_b32_e32 v107, v130, v134, vcc
	v_lshl_add_u64 v[138:139], v[114:115], 0, s[0:1]
	v_cndmask_b32_e32 v111, v131, v135, vcc
	v_mov_b32_dpp v107, v107 quad_perm:[1,0,3,2] row_mask:0xf bank_mask:0xf bound_ctrl:1
	v_cndmask_b32_e32 v119, v126, v136, vcc
	v_cndmask_b32_e32 v124, v127, v137, vcc
	s_mov_b32 s0, 0x11000
	v_mov_b32_dpp v111, v111 quad_perm:[1,0,3,2] row_mask:0xf bank_mask:0xf bound_ctrl:1
	v_mov_b32_dpp v119, v119 quad_perm:[1,0,3,2] row_mask:0xf bank_mask:0xf bound_ctrl:1
	v_mov_b32_dpp v140, v124 quad_perm:[1,0,3,2] row_mask:0xf bank_mask:0xf bound_ctrl:1
	v_cndmask_b32_e32 v124, v107, v130, vcc
	v_add_co_u32_e64 v130, s[0:1], s0, v114
	v_cndmask_b32_e32 v125, v111, v131, vcc
	v_cndmask_b32_e32 v126, v119, v126, vcc
	v_cndmask_b32_e32 v127, v140, v127, vcc
	v_addc_co_u32_e64 v131, s[0:1], 0, v115, s[0:1]
	v_cndmask_b32_e32 v134, v134, v107, vcc
	v_cndmask_b32_e32 v135, v135, v111, vcc
	v_cndmask_b32_e32 v136, v136, v119, vcc
	v_cndmask_b32_e32 v137, v137, v140, vcc
	global_store_dwordx4 v[130:131], v[124:127], off offset:-4096 nt
	global_store_dwordx4 v[130:131], v[134:137], off nt
	v_pk_mul_f32 v[120:121], v[120:121], v[150:151] op_sel_hi:[1,0]
	v_pk_mul_f32 v[124:125], v[128:129], v[150:151] op_sel_hi:[1,0]
	v_pk_mul_f32 v[126:127], v[6:7], v[120:121]
	v_pk_mul_f32 v[120:121], v[4:5], v[124:125]
	v_pk_mul_f32 v[124:125], v[132:133], v[150:151] op_sel_hi:[1,0]
	v_pk_mul_f32 v[122:123], v[122:123], v[150:151] op_sel_hi:[1,0]
	v_pk_mul_f32 v[92:93], v[92:93], v[148:149] op_sel_hi:[1,0]
	v_pk_mul_f32 v[128:129], v[2:3], v[122:123]
	v_pk_mul_f32 v[122:123], v[0:1], v[124:125]
	v_cndmask_b32_e32 v119, v126, v128, vcc
	v_cndmask_b32_e32 v107, v120, v122, vcc
	v_cndmask_b32_e32 v111, v121, v123, vcc
	v_cndmask_b32_e32 v124, v127, v129, vcc
	v_mov_b32_dpp v107, v107 quad_perm:[1,0,3,2] row_mask:0xf bank_mask:0xf bound_ctrl:1
	v_mov_b32_dpp v111, v111 quad_perm:[1,0,3,2] row_mask:0xf bank_mask:0xf bound_ctrl:1
	v_mov_b32_dpp v119, v119 quad_perm:[1,0,3,2] row_mask:0xf bank_mask:0xf bound_ctrl:1
	v_mov_b32_dpp v132, v124 quad_perm:[1,0,3,2] row_mask:0xf bank_mask:0xf bound_ctrl:1
	v_cndmask_b32_e32 v120, v107, v120, vcc
	v_cndmask_b32_e32 v124, v122, v107, vcc
	v_cndmask_b32_e32 v121, v111, v121, vcc
	v_cndmask_b32_e32 v125, v123, v111, vcc
	v_cndmask_b32_e32 v122, v119, v126, vcc
	v_cndmask_b32_e32 v123, v132, v127, vcc
	v_pk_mul_f32 v[88:89], v[88:89], v[148:149] op_sel_hi:[1,0]
	v_pk_mul_f32 v[90:91], v[90:91], v[148:149] op_sel_hi:[1,0]
	v_cndmask_b32_e32 v126, v128, v119, vcc
	v_cndmask_b32_e32 v127, v129, v132, vcc
	global_store_dwordx4 v[138:139], v[120:123], off offset:128 nt
	global_store_dwordx4 v[130:131], v[124:127], off offset:128 nt
	v_pk_mul_f32 v[92:93], v[12:13], v[92:93]
	v_pk_mul_f32 v[122:123], v[10:11], v[90:91]
	v_pk_mul_f32 v[90:91], v[8:9], v[88:89]
	v_pk_mul_f32 v[94:95], v[94:95], v[148:149] op_sel_hi:[1,0]
	v_cndmask_b32_e32 v88, v92, v90, vcc
	v_pk_mul_f32 v[94:95], v[14:15], v[94:95]
	s_mov_b64 s[0:1], 0x20000
	v_mov_b32_dpp v89, v88 quad_perm:[1,0,3,2] row_mask:0xf bank_mask:0xf bound_ctrl:1
	v_cndmask_b32_e32 v88, v93, v91, vcc
	v_lshl_add_u64 v[120:121], v[114:115], 0, s[0:1]
	s_mov_b32 s0, 0x21000
	v_mov_b32_dpp v107, v88 quad_perm:[1,0,3,2] row_mask:0xf bank_mask:0xf bound_ctrl:1
	v_cndmask_b32_e32 v88, v94, v122, vcc
	v_pk_mul_f32 v[84:85], v[84:85], v[148:149] op_sel_hi:[1,0]
	v_pk_mul_f32 v[80:81], v[80:81], v[148:149] op_sel_hi:[1,0]
	v_mov_b32_dpp v111, v88 quad_perm:[1,0,3,2] row_mask:0xf bank_mask:0xf bound_ctrl:1
	v_cndmask_b32_e32 v88, v95, v123, vcc
	v_pk_mul_f32 v[82:83], v[82:83], v[148:149] op_sel_hi:[1,0]
	v_pk_mul_f32 v[84:85], v[4:5], v[84:85]
	v_mov_b32_dpp v119, v88 quad_perm:[1,0,3,2] row_mask:0xf bank_mask:0xf bound_ctrl:1
	v_cndmask_b32_e32 v88, v89, v92, vcc
	v_cndmask_b32_e32 v92, v90, v89, vcc
	v_cndmask_b32_e32 v90, v111, v94, vcc
	v_cndmask_b32_e32 v94, v122, v111, vcc
	v_add_co_u32_e64 v122, s[0:1], s0, v114
	v_cndmask_b32_e32 v89, v107, v93, vcc
	v_cndmask_b32_e32 v93, v91, v107, vcc
	v_cndmask_b32_e32 v91, v119, v95, vcc
	v_cndmask_b32_e32 v95, v123, v119, vcc
	v_addc_co_u32_e64 v123, s[0:1], 0, v115, s[0:1]
	global_store_dwordx4 v[122:123], v[88:91], off offset:-4096 nt
	global_store_dwordx4 v[122:123], v[92:95], off nt
	v_pk_mul_f32 v[86:87], v[86:87], v[148:149] op_sel_hi:[1,0]
	v_pk_mul_f32 v[88:89], v[2:3], v[82:83]
	v_pk_mul_f32 v[82:83], v[0:1], v[80:81]
	v_pk_mul_f32 v[86:87], v[6:7], v[86:87]
	v_cndmask_b32_e32 v80, v84, v82, vcc
	v_pk_mul_f32 v[76:77], v[76:77], v[146:147] op_sel_hi:[1,0]
	v_pk_mul_f32 v[78:79], v[78:79], v[146:147] op_sel_hi:[1,0]
	v_mov_b32_dpp v81, v80 quad_perm:[1,0,3,2] row_mask:0xf bank_mask:0xf bound_ctrl:1
	v_cndmask_b32_e32 v80, v85, v83, vcc
	v_pk_mul_f32 v[78:79], v[14:15], v[78:79]
	s_mov_b64 s[0:1], 0x30000
	v_mov_b32_dpp v90, v80 quad_perm:[1,0,3,2] row_mask:0xf bank_mask:0xf bound_ctrl:1
	v_cndmask_b32_e32 v80, v86, v88, vcc
	v_pk_mul_f32 v[72:73], v[72:73], v[146:147] op_sel_hi:[1,0]
	v_pk_mul_f32 v[74:75], v[74:75], v[146:147] op_sel_hi:[1,0]
	v_mov_b32_dpp v91, v80 quad_perm:[1,0,3,2] row_mask:0xf bank_mask:0xf bound_ctrl:1
	v_cndmask_b32_e32 v80, v87, v89, vcc
	v_pk_mul_f32 v[60:61], v[60:61], v[144:145] op_sel_hi:[1,0]
	v_pk_mul_f32 v[56:57], v[56:57], v[144:145] op_sel_hi:[1,0]
	v_mov_b32_dpp v92, v80 quad_perm:[1,0,3,2] row_mask:0xf bank_mask:0xf bound_ctrl:1
	v_cndmask_b32_e32 v80, v81, v84, vcc
	v_cndmask_b32_e32 v84, v82, v81, vcc
	v_cndmask_b32_e32 v81, v90, v85, vcc
	v_cndmask_b32_e32 v85, v83, v90, vcc
	v_cndmask_b32_e32 v82, v91, v86, vcc
	v_cndmask_b32_e32 v83, v92, v87, vcc
	v_cndmask_b32_e32 v86, v88, v91, vcc
	v_cndmask_b32_e32 v87, v89, v92, vcc
	global_store_dwordx4 v[120:121], v[80:83], off offset:128 nt
	global_store_dwordx4 v[122:123], v[84:87], off offset:128 nt
	v_pk_mul_f32 v[58:59], v[58:59], v[144:145] op_sel_hi:[1,0]
	v_pk_mul_f32 v[80:81], v[100:101], v[146:147] op_sel_hi:[1,0]
	v_pk_mul_f32 v[82:83], v[102:103], v[146:147] op_sel_hi:[1,0]
	v_pk_mul_f32 v[80:81], v[12:13], v[80:81]
	v_pk_mul_f32 v[82:83], v[8:9], v[82:83]
	v_pk_mul_f32 v[86:87], v[10:11], v[76:77]
	v_cndmask_b32_e32 v76, v80, v82, vcc
	v_lshl_add_u64 v[84:85], v[114:115], 0, s[0:1]
	s_mov_b32 s0, 0x31000
	v_mov_b32_dpp v77, v76 quad_perm:[1,0,3,2] row_mask:0xf bank_mask:0xf bound_ctrl:1
	v_cndmask_b32_e32 v76, v81, v83, vcc
	v_pk_mul_f32 v[60:61], v[12:13], v[60:61]
	v_pk_mul_f32 v[62:63], v[62:63], v[144:145] op_sel_hi:[1,0]
	v_mov_b32_dpp v88, v76 quad_perm:[1,0,3,2] row_mask:0xf bank_mask:0xf bound_ctrl:1
	v_cndmask_b32_e32 v76, v78, v86, vcc
	v_pk_mul_f32 v[62:63], v[14:15], v[62:63]
	v_pk_mul_f32 v[52:53], v[52:53], v[144:145] op_sel_hi:[1,0]
	v_mov_b32_dpp v89, v76 quad_perm:[1,0,3,2] row_mask:0xf bank_mask:0xf bound_ctrl:1
	v_cndmask_b32_e32 v76, v79, v87, vcc
	v_cndmask_b32_e32 v78, v89, v78, vcc
	v_pk_mul_f32 v[48:49], v[48:49], v[144:145] op_sel_hi:[1,0]
	v_mov_b32_dpp v90, v76 quad_perm:[1,0,3,2] row_mask:0xf bank_mask:0xf bound_ctrl:1
	v_cndmask_b32_e32 v76, v77, v80, vcc
	v_cndmask_b32_e32 v80, v82, v77, vcc
	v_cndmask_b32_e32 v82, v86, v89, vcc
	v_add_co_u32_e64 v86, s[0:1], s0, v114
	v_cndmask_b32_e32 v77, v88, v81, vcc
	v_cndmask_b32_e32 v81, v83, v88, vcc
	v_cndmask_b32_e32 v79, v90, v79, vcc
	v_cndmask_b32_e32 v83, v87, v90, vcc
	v_addc_co_u32_e64 v87, s[0:1], 0, v115, s[0:1]
	global_store_dwordx4 v[86:87], v[76:79], off offset:-4096 nt
	global_store_dwordx4 v[86:87], v[80:83], off nt
	s_mov_b64 s[0:1], 0x80000
	v_pk_mul_f32 v[76:77], v[96:97], v[146:147] op_sel_hi:[1,0]
	v_pk_mul_f32 v[78:79], v[6:7], v[72:73]
	v_pk_mul_f32 v[72:73], v[4:5], v[76:77]
	v_pk_mul_f32 v[76:77], v[98:99], v[146:147] op_sel_hi:[1,0]
	v_pk_mul_f32 v[80:81], v[2:3], v[74:75]
	v_pk_mul_f32 v[74:75], v[0:1], v[76:77]
	v_cndmask_b32_e32 v82, v78, v80, vcc
	v_cndmask_b32_e32 v76, v72, v74, vcc
	v_cndmask_b32_e32 v77, v73, v75, vcc
	v_cndmask_b32_e32 v83, v79, v81, vcc
	v_mov_b32_dpp v76, v76 quad_perm:[1,0,3,2] row_mask:0xf bank_mask:0xf bound_ctrl:1
	v_mov_b32_dpp v77, v77 quad_perm:[1,0,3,2] row_mask:0xf bank_mask:0xf bound_ctrl:1
	v_mov_b32_dpp v82, v82 quad_perm:[1,0,3,2] row_mask:0xf bank_mask:0xf bound_ctrl:1
	v_mov_b32_dpp v83, v83 quad_perm:[1,0,3,2] row_mask:0xf bank_mask:0xf bound_ctrl:1
	v_cndmask_b32_e32 v72, v76, v72, vcc
	v_cndmask_b32_e32 v76, v74, v76, vcc
	v_cndmask_b32_e32 v73, v77, v73, vcc
	v_cndmask_b32_e32 v77, v75, v77, vcc
	v_cndmask_b32_e32 v74, v82, v78, vcc
	v_cndmask_b32_e32 v75, v83, v79, vcc
	v_cndmask_b32_e32 v78, v80, v82, vcc
	v_cndmask_b32_e32 v79, v81, v83, vcc
	global_store_dwordx4 v[84:85], v[72:75], off offset:128 nt
	global_store_dwordx4 v[86:87], v[76:79], off offset:128 nt
	v_pk_mul_f32 v[50:51], v[50:51], v[144:145] op_sel_hi:[1,0]
	v_pk_mul_f32 v[74:75], v[10:11], v[58:59]
	v_pk_mul_f32 v[58:59], v[8:9], v[56:57]
	v_lshl_add_u64 v[72:73], v[114:115], 0, s[0:1]
	v_cndmask_b32_e32 v56, v60, v58, vcc
	s_mov_b32 s0, 0x81000
	v_pk_mul_f32 v[52:53], v[4:5], v[52:53]
	v_mov_b32_dpp v57, v56 quad_perm:[1,0,3,2] row_mask:0xf bank_mask:0xf bound_ctrl:1
	v_cndmask_b32_e32 v56, v61, v59, vcc
	v_pk_mul_f32 v[54:55], v[54:55], v[144:145] op_sel_hi:[1,0]
	v_pk_mul_f32 v[44:45], v[44:45], v[118:119] op_sel_hi:[1,0]
	v_mov_b32_dpp v76, v56 quad_perm:[1,0,3,2] row_mask:0xf bank_mask:0xf bound_ctrl:1
	v_cndmask_b32_e32 v56, v62, v74, vcc
	v_pk_mul_f32 v[54:55], v[6:7], v[54:55]
	v_pk_mul_f32 v[46:47], v[46:47], v[118:119] op_sel_hi:[1,0]
	v_mov_b32_dpp v77, v56 quad_perm:[1,0,3,2] row_mask:0xf bank_mask:0xf bound_ctrl:1
	v_cndmask_b32_e32 v56, v63, v75, vcc
	v_pk_mul_f32 v[46:47], v[14:15], v[46:47]
	v_pk_mul_f32 v[40:41], v[40:41], v[118:119] op_sel_hi:[1,0]
	v_mov_b32_dpp v78, v56 quad_perm:[1,0,3,2] row_mask:0xf bank_mask:0xf bound_ctrl:1
	v_cndmask_b32_e32 v56, v57, v60, vcc
	v_cndmask_b32_e32 v60, v58, v57, vcc
	v_cndmask_b32_e32 v58, v77, v62, vcc
	v_cndmask_b32_e32 v62, v74, v77, vcc
	v_add_co_u32_e64 v74, s[0:1], s0, v114
	v_cndmask_b32_e32 v57, v76, v61, vcc
	v_cndmask_b32_e32 v61, v59, v76, vcc
	v_cndmask_b32_e32 v59, v78, v63, vcc
	v_cndmask_b32_e32 v63, v75, v78, vcc
	v_addc_co_u32_e64 v75, s[0:1], 0, v115, s[0:1]
	global_store_dwordx4 v[74:75], v[56:59], off offset:-4096 nt
	global_store_dwordx4 v[74:75], v[60:63], off nt
	s_mov_b64 s[0:1], 0x90000
	v_pk_mul_f32 v[56:57], v[2:3], v[50:51]
	v_pk_mul_f32 v[50:51], v[0:1], v[48:49]
	v_pk_mul_f32 v[42:43], v[42:43], v[118:119] op_sel_hi:[1,0]
	v_cndmask_b32_e32 v48, v52, v50, vcc
	v_pk_mul_f32 v[28:29], v[28:29], v[110:111] op_sel_hi:[1,0]
	v_pk_mul_f32 v[24:25], v[24:25], v[110:111] op_sel_hi:[1,0]
	v_mov_b32_dpp v49, v48 quad_perm:[1,0,3,2] row_mask:0xf bank_mask:0xf bound_ctrl:1
	v_cndmask_b32_e32 v48, v53, v51, vcc
	v_pk_mul_f32 v[26:27], v[26:27], v[110:111] op_sel_hi:[1,0]
	v_pk_mul_f32 v[28:29], v[12:13], v[28:29]
	v_mov_b32_dpp v58, v48 quad_perm:[1,0,3,2] row_mask:0xf bank_mask:0xf bound_ctrl:1
	v_cndmask_b32_e32 v48, v54, v56, vcc
	v_pk_mul_f32 v[30:31], v[30:31], v[110:111] op_sel_hi:[1,0]
	v_pk_mul_f32 v[20:21], v[20:21], v[110:111] op_sel_hi:[1,0]
	v_mov_b32_dpp v59, v48 quad_perm:[1,0,3,2] row_mask:0xf bank_mask:0xf bound_ctrl:1
	v_cndmask_b32_e32 v48, v55, v57, vcc
	v_pk_mul_f32 v[30:31], v[14:15], v[30:31]
	v_pk_mul_f32 v[16:17], v[16:17], v[110:111] op_sel_hi:[1,0]
	v_mov_b32_dpp v60, v48 quad_perm:[1,0,3,2] row_mask:0xf bank_mask:0xf bound_ctrl:1
	v_cndmask_b32_e32 v48, v49, v52, vcc
	v_cndmask_b32_e32 v52, v50, v49, vcc
	v_cndmask_b32_e32 v49, v58, v53, vcc
	v_cndmask_b32_e32 v53, v51, v58, vcc
	v_cndmask_b32_e32 v50, v59, v54, vcc
	v_cndmask_b32_e32 v51, v60, v55, vcc
	v_cndmask_b32_e32 v54, v56, v59, vcc
	v_cndmask_b32_e32 v55, v57, v60, vcc
	global_store_dwordx4 v[72:73], v[48:51], off offset:128 nt
	global_store_dwordx4 v[74:75], v[52:55], off offset:128 nt
	v_pk_mul_f32 v[18:19], v[18:19], v[110:111] op_sel_hi:[1,0]
	v_pk_mul_f32 v[48:49], v[68:69], v[118:119] op_sel_hi:[1,0]
	v_pk_mul_f32 v[50:51], v[70:71], v[118:119] op_sel_hi:[1,0]
	v_pk_mul_f32 v[48:49], v[12:13], v[48:49]
	v_pk_mul_f32 v[50:51], v[8:9], v[50:51]
	v_pk_mul_f32 v[54:55], v[10:11], v[44:45]
	v_cndmask_b32_e32 v44, v48, v50, vcc
	v_lshl_add_u64 v[52:53], v[114:115], 0, s[0:1]
	s_mov_b32 s0, 0x91000
	v_mov_b32_dpp v45, v44 quad_perm:[1,0,3,2] row_mask:0xf bank_mask:0xf bound_ctrl:1
	v_cndmask_b32_e32 v44, v49, v51, vcc
	v_pk_mul_f32 v[20:21], v[4:5], v[20:21]
	v_pk_mul_f32 v[22:23], v[22:23], v[110:111] op_sel_hi:[1,0]
	v_mov_b32_dpp v56, v44 quad_perm:[1,0,3,2] row_mask:0xf bank_mask:0xf bound_ctrl:1
	v_cndmask_b32_e32 v44, v46, v54, vcc
	s_waitcnt vmcnt(20)
	v_fmamk_f32 v106, v106, 0x3a800000, v222
	v_pk_mul_f32 v[22:23], v[6:7], v[22:23]
	v_mov_b32_dpp v57, v44 quad_perm:[1,0,3,2] row_mask:0xf bank_mask:0xf bound_ctrl:1
	v_cndmask_b32_e32 v44, v47, v55, vcc
	v_cndmask_b32_e32 v46, v57, v46, vcc
	v_rsq_f32_e32 v106, v106
	v_mov_b32_dpp v58, v44 quad_perm:[1,0,3,2] row_mask:0xf bank_mask:0xf bound_ctrl:1
	v_cndmask_b32_e32 v44, v45, v48, vcc
	v_cndmask_b32_e32 v48, v50, v45, vcc
	v_cndmask_b32_e32 v50, v54, v57, vcc
	v_add_co_u32_e64 v54, s[0:1], s0, v114
	v_cndmask_b32_e32 v45, v56, v49, vcc
	v_cndmask_b32_e32 v49, v51, v56, vcc
	v_cndmask_b32_e32 v47, v58, v47, vcc
	v_cndmask_b32_e32 v51, v55, v58, vcc
	v_addc_co_u32_e64 v55, s[0:1], 0, v115, s[0:1]
	global_store_dwordx4 v[54:55], v[44:47], off offset:-4096 nt
	global_store_dwordx4 v[54:55], v[48:51], off nt
	s_mov_b64 s[0:1], 0xa0000
	v_pk_mul_f32 v[44:45], v[64:65], v[118:119] op_sel_hi:[1,0]
	v_pk_mul_f32 v[46:47], v[6:7], v[40:41]
	v_pk_mul_f32 v[40:41], v[4:5], v[44:45]
	v_pk_mul_f32 v[44:45], v[66:67], v[118:119] op_sel_hi:[1,0]
	v_pk_mul_f32 v[48:49], v[2:3], v[42:43]
	v_pk_mul_f32 v[42:43], v[0:1], v[44:45]
	v_cndmask_b32_e32 v50, v46, v48, vcc
	v_cndmask_b32_e32 v44, v40, v42, vcc
	v_cndmask_b32_e32 v45, v41, v43, vcc
	v_cndmask_b32_e32 v51, v47, v49, vcc
	v_mov_b32_dpp v44, v44 quad_perm:[1,0,3,2] row_mask:0xf bank_mask:0xf bound_ctrl:1
	v_mov_b32_dpp v45, v45 quad_perm:[1,0,3,2] row_mask:0xf bank_mask:0xf bound_ctrl:1
	v_mov_b32_dpp v50, v50 quad_perm:[1,0,3,2] row_mask:0xf bank_mask:0xf bound_ctrl:1
	v_mov_b32_dpp v51, v51 quad_perm:[1,0,3,2] row_mask:0xf bank_mask:0xf bound_ctrl:1
	v_cndmask_b32_e32 v40, v44, v40, vcc
	v_cndmask_b32_e32 v44, v42, v44, vcc
	v_cndmask_b32_e32 v41, v45, v41, vcc
	v_cndmask_b32_e32 v45, v43, v45, vcc
	v_cndmask_b32_e32 v42, v50, v46, vcc
	v_cndmask_b32_e32 v43, v51, v47, vcc
	v_cndmask_b32_e32 v46, v48, v50, vcc
	v_cndmask_b32_e32 v47, v49, v51, vcc
	global_store_dwordx4 v[52:53], v[40:43], off offset:128 nt
	global_store_dwordx4 v[54:55], v[44:47], off offset:128 nt
	s_nop 0
	v_pk_mul_f32 v[42:43], v[10:11], v[26:27]
	v_pk_mul_f32 v[26:27], v[8:9], v[24:25]
	v_lshl_add_u64 v[40:41], v[114:115], 0, s[0:1]
	v_cndmask_b32_e32 v24, v28, v26, vcc
	s_mov_b32 s0, 0xa1000
	s_nop 0
	v_mov_b32_dpp v25, v24 quad_perm:[1,0,3,2] row_mask:0xf bank_mask:0xf bound_ctrl:1
	v_cndmask_b32_e32 v24, v29, v27, vcc
	s_nop 1
	v_mov_b32_dpp v44, v24 quad_perm:[1,0,3,2] row_mask:0xf bank_mask:0xf bound_ctrl:1
	v_cndmask_b32_e32 v24, v30, v42, vcc
	s_nop 1
	v_mov_b32_dpp v45, v24 quad_perm:[1,0,3,2] row_mask:0xf bank_mask:0xf bound_ctrl:1
	v_cndmask_b32_e32 v24, v31, v43, vcc
	s_nop 1
	v_mov_b32_dpp v46, v24 quad_perm:[1,0,3,2] row_mask:0xf bank_mask:0xf bound_ctrl:1
	v_cndmask_b32_e32 v24, v25, v28, vcc
	v_cndmask_b32_e32 v28, v26, v25, vcc
	v_cndmask_b32_e32 v26, v45, v30, vcc
	v_cndmask_b32_e32 v30, v42, v45, vcc
	v_add_co_u32_e64 v42, s[0:1], s0, v114
	v_cndmask_b32_e32 v25, v44, v29, vcc
	v_cndmask_b32_e32 v29, v27, v44, vcc
	v_cndmask_b32_e32 v27, v46, v31, vcc
	v_cndmask_b32_e32 v31, v43, v46, vcc
	v_addc_co_u32_e64 v43, s[0:1], 0, v115, s[0:1]
	global_store_dwordx4 v[42:43], v[24:27], off offset:-4096 nt
	global_store_dwordx4 v[42:43], v[28:31], off nt
	s_mov_b64 s[0:1], 0xb0000
	v_pk_mul_f32 v[24:25], v[2:3], v[18:19]
	v_pk_mul_f32 v[18:19], v[0:1], v[16:17]
	s_nop 0
	v_cndmask_b32_e32 v16, v20, v18, vcc
	s_nop 1
	v_mov_b32_dpp v17, v16 quad_perm:[1,0,3,2] row_mask:0xf bank_mask:0xf bound_ctrl:1
	v_cndmask_b32_e32 v16, v21, v19, vcc
	s_nop 1
	v_mov_b32_dpp v26, v16 quad_perm:[1,0,3,2] row_mask:0xf bank_mask:0xf bound_ctrl:1
	v_cndmask_b32_e32 v16, v22, v24, vcc
	s_nop 1
	v_mov_b32_dpp v27, v16 quad_perm:[1,0,3,2] row_mask:0xf bank_mask:0xf bound_ctrl:1
	v_cndmask_b32_e32 v16, v23, v25, vcc
	s_nop 1
	v_mov_b32_dpp v28, v16 quad_perm:[1,0,3,2] row_mask:0xf bank_mask:0xf bound_ctrl:1
	v_cndmask_b32_e32 v16, v17, v20, vcc
	v_cndmask_b32_e32 v20, v18, v17, vcc
	v_cndmask_b32_e32 v17, v26, v21, vcc
	v_cndmask_b32_e32 v21, v19, v26, vcc
	v_cndmask_b32_e32 v18, v27, v22, vcc
	v_cndmask_b32_e32 v19, v28, v23, vcc
	v_cndmask_b32_e32 v22, v24, v27, vcc
	v_cndmask_b32_e32 v23, v25, v28, vcc
	global_store_dwordx4 v[40:41], v[16:19], off offset:128 nt
	global_store_dwordx4 v[42:43], v[20:23], off offset:128 nt
	s_nop 0
	v_pk_mul_f32 v[18:19], v[116:117], v[106:107] op_sel_hi:[1,0]
	v_pk_mul_f32 v[20:21], v[36:37], v[106:107] op_sel_hi:[1,0]
	v_pk_mul_f32 v[12:13], v[12:13], v[18:19]
	v_pk_mul_f32 v[14:15], v[14:15], v[20:21]
	v_pk_mul_f32 v[18:19], v[112:113], v[106:107] op_sel_hi:[1,0]
	v_pk_mul_f32 v[20:21], v[38:39], v[106:107] op_sel_hi:[1,0]
	v_lshl_add_u64 v[16:17], v[114:115], 0, s[0:1]
	v_pk_mul_f32 v[20:21], v[10:11], v[20:21]
	v_pk_mul_f32 v[10:11], v[8:9], v[18:19]
	s_mov_b32 s0, 0xb1000
	v_cndmask_b32_e32 v8, v12, v10, vcc
	s_nop 1
	v_mov_b32_dpp v9, v8 quad_perm:[1,0,3,2] row_mask:0xf bank_mask:0xf bound_ctrl:1
	v_cndmask_b32_e32 v8, v13, v11, vcc
	s_nop 1
	v_mov_b32_dpp v18, v8 quad_perm:[1,0,3,2] row_mask:0xf bank_mask:0xf bound_ctrl:1
	v_cndmask_b32_e32 v8, v14, v20, vcc
	s_nop 1
	v_mov_b32_dpp v19, v8 quad_perm:[1,0,3,2] row_mask:0xf bank_mask:0xf bound_ctrl:1
	v_cndmask_b32_e32 v8, v15, v21, vcc
	s_nop 1
	v_mov_b32_dpp v22, v8 quad_perm:[1,0,3,2] row_mask:0xf bank_mask:0xf bound_ctrl:1
	v_cndmask_b32_e32 v8, v9, v12, vcc
	v_cndmask_b32_e32 v12, v10, v9, vcc
	v_cndmask_b32_e32 v9, v18, v13, vcc
	v_cndmask_b32_e32 v13, v11, v18, vcc
	v_add_co_u32_e64 v18, s[0:1], s0, v114
	v_cndmask_b32_e32 v10, v19, v14, vcc
	v_cndmask_b32_e32 v14, v20, v19, vcc
	v_cndmask_b32_e32 v11, v22, v15, vcc
	v_addc_co_u32_e64 v19, s[0:1], 0, v115, s[0:1]
	v_cndmask_b32_e32 v15, v21, v22, vcc
	global_store_dwordx4 v[18:19], v[8:11], off offset:-4096 nt
	global_store_dwordx4 v[18:19], v[12:15], off nt
	s_mov_b64 s[0:1], -1
	v_pk_mul_f32 v[8:9], v[108:109], v[106:107] op_sel_hi:[1,0]
	v_pk_mul_f32 v[10:11], v[32:33], v[106:107] op_sel_hi:[1,0]
	v_pk_mul_f32 v[4:5], v[4:5], v[8:9]
	v_pk_mul_f32 v[6:7], v[6:7], v[10:11]
	v_pk_mul_f32 v[8:9], v[104:105], v[106:107] op_sel_hi:[1,0]
	v_pk_mul_f32 v[10:11], v[34:35], v[106:107] op_sel_hi:[1,0]
	s_nop 0
	v_pk_mul_f32 v[10:11], v[2:3], v[10:11]
	v_pk_mul_f32 v[2:3], v[0:1], v[8:9]
	s_nop 0
	v_cndmask_b32_e32 v0, v4, v2, vcc
	s_nop 1
	v_mov_b32_dpp v1, v0 quad_perm:[1,0,3,2] row_mask:0xf bank_mask:0xf bound_ctrl:1
	v_cndmask_b32_e32 v0, v5, v3, vcc
	s_nop 1
	v_mov_b32_dpp v8, v0 quad_perm:[1,0,3,2] row_mask:0xf bank_mask:0xf bound_ctrl:1
	v_cndmask_b32_e32 v0, v6, v10, vcc
	s_nop 1
	v_mov_b32_dpp v9, v0 quad_perm:[1,0,3,2] row_mask:0xf bank_mask:0xf bound_ctrl:1
	v_cndmask_b32_e32 v0, v7, v11, vcc
	s_nop 1
	v_mov_b32_dpp v12, v0 quad_perm:[1,0,3,2] row_mask:0xf bank_mask:0xf bound_ctrl:1
	v_cndmask_b32_e32 v0, v1, v4, vcc
	v_cndmask_b32_e32 v4, v2, v1, vcc
	v_cndmask_b32_e32 v1, v8, v5, vcc
	v_cndmask_b32_e32 v5, v3, v8, vcc
	v_cndmask_b32_e32 v2, v9, v6, vcc
	v_cndmask_b32_e32 v6, v10, v9, vcc
	v_cndmask_b32_e32 v3, v12, v7, vcc
	v_cndmask_b32_e32 v7, v11, v12, vcc
	s_andn2_b64 vcc, exec, s[38:39]
	global_store_dwordx4 v[16:17], v[0:3], off offset:128 nt
	global_store_dwordx4 v[18:19], v[4:7], off offset:128 nt
	s_cbranch_vccnz .LBB0_250
	s_andn2_b64 vcc, exec, s[4:5]
	s_cbranch_vccnz .LBB0_249
	s_barrier
	s_branch .LBB0_249

.LBB0_614:
	ds_read_b128 v[4:7], v2
	v_add_u32_e32 v3, 0x200, v3
	s_movk_i32 s54, 0x1bf
	v_ashrrev_i32_e32 v1, 31, v0
	v_cmp_lt_i32_e32 vcc, s54, v3
	v_add_u32_e32 v2, 0x2000, v2
	v_lshl_add_u64 v[8:9], v[0:1], 2, s[34:35]
	v_add_u32_e32 v0, 0x800, v0
	s_or_b64 s[38:39], vcc, s[38:39]
	s_waitcnt lgkmcnt(0)
	global_store_dwordx4 v[8:9], v[4:7], off nt
	s_andn2_b64 exec, exec, s[38:39]
	s_cbranch_execnz .LBB0_614
